# P0 row pass: wave sums via DPP quad_perm/mirror adds + permlane swaps instead of 12 ds_bpermute round trips per iteration
# baseline (speedup 1.0000x reference)
.LBB0_47:
	s_waitcnt vmcnt(3)
	v_pk_mul_f32 v[38:39], v[28:29], v[28:29]
	v_pk_mul_f32 v[40:41], v[26:27], v[26:27]
	v_mov_b32_e32 v43, v39
	v_mov_b32_e32 v42, v40
	v_pk_mov_b32 v[38:39], v[40:41], v[38:39] op_sel:[1,0]
	v_pk_mul_f32 v[40:41], v[18:19], v[18:19]
	v_pk_add_f32 v[38:39], v[38:39], v[42:43]
	v_pk_mul_f32 v[42:43], v[20:21], v[20:21]
	v_mov_b32_e32 v44, v40
	v_mov_b32_e32 v45, v43
	v_pk_mov_b32 v[40:41], v[40:41], v[42:43] op_sel:[1,0]
	s_waitcnt vmcnt(2)
	v_pk_mul_f32 v[42:43], v[32:33], v[32:33]
	v_pk_add_f32 v[40:41], v[40:41], v[44:45]
	v_pk_mul_f32 v[44:45], v[30:31], v[30:31]
	v_mov_b32_e32 v55, v43
	v_mov_b32_e32 v54, v44
	v_pk_mov_b32 v[42:43], v[44:45], v[42:43] op_sel:[1,0]
	v_pk_mul_f32 v[44:45], v[6:7], v[6:7]
	v_pk_add_f32 v[42:43], v[42:43], v[54:55]
	v_pk_mul_f32 v[54:55], v[8:9], v[8:9]
	v_mov_b32_e32 v56, v44
	v_pk_mov_b32 v[44:45], v[44:45], v[54:55] op_sel:[1,0]
	s_waitcnt vmcnt(0)
	v_mul_f32_e32 v53, v14, v14
	v_mul_f32_e32 v54, v15, v15
	v_pk_add_f32 v[38:39], v[38:39], v[38:39] op_sel:[0,1] op_sel_hi:[1,0]
	v_pk_add_f32 v[42:43], v[42:43], v[42:43] op_sel:[0,1] op_sel_hi:[1,0]
	v_mov_b32_e32 v39, v53
	v_mov_b32_e32 v43, v54
	v_pk_add_f32 v[38:39], v[38:39], v[42:43]
	v_mul_f32_e32 v42, v23, v23
	v_mov_b32_e32 v57, v55
	v_mul_f32_e32 v55, v16, v16
	v_pk_fma_f32 v[42:43], v[22:23], v[22:23], v[42:43] op_sel_hi:[1,1,0]
	v_mul_f32_e32 v54, v25, v25
	v_pk_add_f32 v[44:45], v[44:45], v[56:57]
	v_mul_f32_e32 v56, v17, v17
	v_mov_b32_e32 v43, v55
	v_pk_fma_f32 v[54:55], v[24:25], v[24:25], v[54:55] op_sel_hi:[1,1,0]
	s_lshl_b64 s[20:21], s[4:5], 11
	v_mov_b32_e32 v55, v56
	v_pk_add_f32 v[42:43], v[42:43], v[54:55]
	v_mul_f32_e32 v54, v4, v4
	v_pk_add_f32 v[38:39], v[38:39], v[42:43]
	v_mul_f32_e32 v42, v2, v2
	v_add_f32_e32 v53, v38, v39
	v_pk_add_f32 v[38:39], v[40:41], v[40:41] op_sel:[0,1] op_sel_hi:[1,0]
	v_pk_add_f32 v[40:41], v[44:45], v[44:45] op_sel:[0,1] op_sel_hi:[1,0]

	v_mul_f32_e32 v43, v3, v3
	v_mov_b32_e32 v39, v42
	v_mov_b32_e32 v41, v43
	v_pk_add_f32 v[38:39], v[38:39], v[40:41]
	s_waitcnt lgkmcnt(0)
	s_nop 1
	v_add_f32_dpp v44, v53, v53 quad_perm:[1,0,3,2] row_mask:0xf bank_mask:0xf

	v_mul_f32_e32 v40, v11, v11
	v_mul_f32_e32 v42, v13, v13
	v_mul_f32_e32 v55, v5, v5
	v_pk_fma_f32 v[40:41], v[10:11], v[10:11], v[40:41] op_sel_hi:[1,1,0]
	v_pk_fma_f32 v[42:43], v[12:13], v[12:13], v[42:43] op_sel_hi:[1,1,0]
	v_mov_b32_e32 v41, v54
	v_mov_b32_e32 v43, v55
	v_pk_add_f32 v[40:41], v[40:41], v[42:43]
	s_lshl_b64 s[22:23], s[14:15], 11
	v_pk_add_f32 v[38:39], v[38:39], v[40:41]
	s_waitcnt lgkmcnt(0)
	s_nop 1
	v_add_f32_dpp v40, v44, v44 quad_perm:[2,3,0,1] row_mask:0xf bank_mask:0xf

	v_add_f32_e32 v38, v38, v39

	s_waitcnt lgkmcnt(1)
	s_nop 1
	v_add_f32_dpp v40, v40, v40 row_half_mirror row_mask:0xf bank_mask:0xf

	s_waitcnt lgkmcnt(1)
	s_nop 1
	v_add_f32_dpp v38, v38, v38 quad_perm:[1,0,3,2] row_mask:0xf bank_mask:0xf

	s_waitcnt lgkmcnt(1)
	s_nop 1
	v_add_f32_dpp v40, v40, v40 row_mirror row_mask:0xf bank_mask:0xf
	v_mov_b32_e32 v41, v40
	s_nop 1
	v_permlane16_swap_b32_e32 v40, v41
	s_waitcnt lgkmcnt(1)
	s_nop 1
	v_add_f32_dpp v38, v38, v38 quad_perm:[2,3,0,1] row_mask:0xf bank_mask:0xf

	s_waitcnt lgkmcnt(1)
	v_add_f32_e32 v40, v40, v41
	v_mov_b32_e32 v41, v40
	s_nop 1
	v_permlane32_swap_b32_e32 v40, v41
	s_waitcnt lgkmcnt(1)
	s_nop 1
	v_add_f32_dpp v38, v38, v38 row_half_mirror row_mask:0xf bank_mask:0xf

	s_waitcnt lgkmcnt(1)
	v_add_f32_e32 v40, v40, v41
	v_fmamk_f32 v40, v40, 0x3a800000, v51
	v_mul_f32_e32 v41, 0x4f800000, v40
	v_cmp_gt_f32_e32 vcc, s18, v40
	s_waitcnt lgkmcnt(0)
	s_nop 1
	v_add_f32_dpp v38, v38, v38 row_mirror row_mask:0xf bank_mask:0xf
	v_mov_b32_e32 v39, v38
	s_nop 1
	v_permlane16_swap_b32_e32 v38, v39
	v_cndmask_b32_e32 v40, v40, v41, vcc
	v_sqrt_f32_e32 v41, v40
	s_waitcnt lgkmcnt(0)
	v_add_f32_e32 v38, v38, v39
	v_add_u32_e32 v42, -1, v41
	v_fma_f32 v43, -v42, v41, v40
	v_cmp_ge_f32_e64 s[8:9], 0, v43
	v_add_u32_e32 v43, 1, v41
	v_mov_b32_e32 v39, v38
	s_nop 1
	v_permlane32_swap_b32_e32 v38, v39
	v_cndmask_b32_e64 v42, v41, v42, s[8:9]
	v_fma_f32 v41, -v43, v41, v40
	v_cmp_lt_f32_e64 s[8:9], 0, v41
	s_waitcnt lgkmcnt(0)
	v_add_f32_e32 v38, v38, v39
	v_cndmask_b32_e64 v41, v42, v43, s[8:9]
	v_mul_f32_e32 v42, 0x37800000, v41
	v_cndmask_b32_e32 v41, v41, v42, vcc
	v_cmp_class_f32_e32 vcc, v40, v52
	v_fmamk_f32 v38, v38, 0x3a800000, v51
	v_mul_f32_e32 v44, 0x4f800000, v38
	v_cndmask_b32_e32 v40, v41, v40, vcc
	v_div_scale_f32 v41, s[8:9], v40, v40, 1.0
	v_rcp_f32_e32 v42, v41
	v_cmp_gt_f32_e64 s[8:9], s18, v38
	v_fma_f32 v39, -v41, v42, 1.0
	s_nop 0
	v_cndmask_b32_e64 v38, v38, v44, s[8:9]
	v_fmac_f32_e32 v42, v39, v42
	v_div_scale_f32 v39, vcc, 1.0, v40, 1.0
	v_sqrt_f32_e32 v44, v38
	v_mul_f32_e32 v43, v39, v42
	v_fma_f32 v45, -v41, v43, v39
	v_fmac_f32_e32 v43, v45, v42
	v_fma_f32 v39, -v41, v43, v39
	v_add_u32_e32 v41, -1, v44
	v_fma_f32 v45, -v41, v44, v38
	v_cmp_ge_f32_e64 s[10:11], 0, v45
	v_add_u32_e32 v45, 1, v44
	s_nop 0
	v_cndmask_b32_e64 v41, v44, v41, s[10:11]
	v_fma_f32 v44, -v45, v44, v38
	v_cmp_lt_f32_e64 s[10:11], 0, v44
	s_nop 1
	v_cndmask_b32_e64 v41, v41, v45, s[10:11]
	v_mul_f32_e32 v44, 0x37800000, v41
	v_cndmask_b32_e64 v41, v41, v44, s[8:9]
	v_cmp_class_f32_e64 s[8:9], v38, v52
	s_nop 1
	v_cndmask_b32_e64 v41, v41, v38, s[8:9]
	v_div_scale_f32 v44, s[8:9], v41, v41, 1.0
	v_rcp_f32_e32 v45, v44
	v_div_fmas_f32 v38, v39, v42, v43
	v_div_fixup_f32 v38, v38, v40, 1.0
	v_fma_f32 v39, -v44, v45, 1.0
	v_fmac_f32_e32 v45, v39, v45
	v_div_scale_f32 v39, vcc, 1.0, v41, 1.0
	v_mul_f32_e32 v40, v39, v45
	v_fma_f32 v42, -v44, v40, v39
	v_fmac_f32_e32 v40, v42, v45
	v_fma_f32 v39, -v44, v40, v39
	v_div_fmas_f32 v39, v39, v45, v40
	v_div_fixup_f32 v40, v39, v41, 1.0
	v_pk_mul_f32 v[28:29], v[28:29], v[38:39] op_sel_hi:[1,0]
	v_pk_mul_f32 v[26:27], v[26:27], v[38:39] op_sel_hi:[1,0]
	v_lshl_add_u64 v[44:45], v[36:37], 0, s[20:21]
	v_lshl_add_u64 v[42:43], v[36:37], 0, s[22:23]
	v_mov_b32_e32 v41, v40
	v_cvt_pk_bf16_f32 v26, v26, v27
	v_cvt_pk_bf16_f32 v27, v28, v29
	s_and_b64 vcc, exec, s[6:7]
	global_store_dwordx2 v[44:45], v[26:27], off
	s_cbranch_vccnz .LBB0_49
	v_mov_b32_e32 v26, v40
	v_mov_b32_e32 v27, v40
	v_pk_mul_f32 v[20:21], v[20:21], v[26:27]
	v_pk_mul_f32 v[18:19], v[18:19], v[40:41]
	s_nop 0
	v_cvt_pk_bf16_f32 v18, v18, v19
	v_cvt_pk_bf16_f32 v19, v20, v21
	global_store_dwordx2 v[42:43], v[18:19], off
